# grid barriers: the XCD leader releases its local workgroups (generation add) before its own wait + cache invalidate instead of after
# speedup vs baseline: 1.0077x; 1.0077x over previous
.LBB0_205:
	s_or_b64 exec, exec, s[8:9]
	s_mov_b64 s[8:9], exec
	v_mbcnt_lo_u32_b32 v0, s8, 0
	v_mbcnt_hi_u32_b32 v0, s9, v0
	v_cmp_eq_u32_e32 vcc, 0, v0
	s_and_saveexec_b64 s[14:15], vcc
	s_cbranch_execz .LBB0_207
	s_bcnt1_i32_b64 s3, s[8:9]
	v_mov_b32_e32 v0, 0x2000
	v_mov_b32_e32 v1, s3
	global_atomic_add v0, v1, s[4:5] offset:1024
.LBB0_207:
	s_or_b64 exec, exec, s[14:15]
	s_waitcnt vmcnt(0)
	buffer_inv sc1
	s_waitcnt vmcnt(0)
.LBB0_208:
	s_or_b64 exec, exec, s[0:1]
	v_mov_b32_e32 v108, v184
	s_waitcnt lgkmcnt(0)
	s_barrier
	s_cmp_gt_i32 s2, 2
	v_readfirstlane_b32 s3, v108
	s_cbranch_scc1 .LBB0_214
	s_waitcnt vmcnt(13)
	v_add_u32_e32 v8, 0x1000, v108
	v_ashrrev_i32_e32 v109, 31, v108
	v_readlane_b32 s36, v254, 26
	v_readlane_b32 s20, v254, 0
	v_ashrrev_i32_e32 v9, 31, v8
	s_movk_i32 s0, 0x800
	v_lshlrev_b64 v[6:7], 2, v[108:109]
	v_readlane_b32 s38, v254, 28
	v_readlane_b32 s39, v254, 29
	v_readlane_b32 s50, v254, 40
	v_readlane_b32 s51, v254, 41
	v_readlane_b32 s21, v254, 1
	v_readlane_b32 s22, v254, 2
	v_readlane_b32 s23, v254, 3
	v_lshl_add_u64 v[8:9], v[8:9], 2, s[28:29]
	s_mov_b64 s[14:15], 0x100000
	v_cmp_gt_i32_e64 s[0:1], s0, v108
	s_waitcnt vmcnt(11)
	v_add_u32_e32 v16, 0xfffffe00, v108
	v_lshl_add_u64 v[0:1], s[70:71], 0, v[6:7]
	v_lshl_add_u64 v[2:3], s[28:29], 0, v[6:7]
	s_mul_i32 s4, s2, 0x1800
	s_mul_i32 s16, s30, 0x1800
	s_mov_b64 s[38:39], s[80:81]
	v_lshl_add_u64 v[4:5], s[50:51], 0, v[6:7]
	s_mul_i32 s8, s2, 0x3000
	s_mul_i32 s17, s30, 0x3000
	v_lshl_add_u64 v[6:7], s[20:21], 0, v[6:7]
	v_lshl_add_u64 v[8:9], v[8:9], 0, s[14:15]
	s_movk_i32 s22, 0x5ff
	s_mov_b32 s23, s2
	v_readlane_b32 s37, v254, 27
	v_readlane_b32 s40, v254, 30
	v_readlane_b32 s41, v254, 31
	v_readlane_b32 s42, v254, 32
	v_readlane_b32 s43, v254, 33
	v_readlane_b32 s44, v254, 34
	v_readlane_b32 s45, v254, 35
	v_readlane_b32 s46, v254, 36
	v_readlane_b32 s47, v254, 37
	v_readlane_b32 s48, v254, 38
	v_readlane_b32 s49, v254, 39
	v_readlane_b32 s24, v254, 4
	v_readlane_b32 s25, v254, 5
	v_readlane_b32 s26, v254, 6
	v_readlane_b32 s27, v254, 7
	s_branch .LBB0_211

.LBB0_282:
	s_or_b64 exec, exec, s[6:7]
	s_mov_b64 s[6:7], exec
	v_mbcnt_lo_u32_b32 v0, s6, 0
	v_mbcnt_hi_u32_b32 v0, s7, v0
	v_cmp_eq_u32_e32 vcc, 0, v0
	s_and_saveexec_b64 s[8:9], vcc
	s_cbranch_execz .LBB0_284
	s_bcnt1_i32_b64 s3, s[6:7]
	v_mov_b32_e32 v0, 0x2000
	v_mov_b32_e32 v1, s3
	global_atomic_add v0, v1, s[4:5] offset:1024
.LBB0_284:
	s_or_b64 exec, exec, s[8:9]
	s_waitcnt vmcnt(0)
	buffer_inv sc1
	s_waitcnt vmcnt(0)
.LBB0_285:
	s_or_b64 exec, exec, s[0:1]
	s_waitcnt vmcnt(13)
	v_mov_b32_e32 v8, v184
	s_cmpk_lt_i32 s2, 0x200
	s_waitcnt lgkmcnt(0)
	s_barrier
	s_cselect_b64 s[0:1], -1, 0
	s_cmpk_gt_i32 s2, 0x1ff
	v_readfirstlane_b32 s4, v8
	s_cbranch_scc1 .LBB0_287
	s_ashr_i32 s3, s2, 31
	s_lshr_b32 s3, s3, 26
	s_add_i32 s3, s2, s3
	s_ashr_i32 s5, s3, 6
	s_andn2_b32 s3, s3, 63
	s_sub_i32 s3, s2, s3
	s_bfe_i32 s6, s3, 0x80000
	s_bfe_u32 s6, s6, 0x2000d
	s_add_i32 s6, s3, s6
	s_bfe_i32 s7, s6, 0x80000
	s_and_b32 s6, s6, 0xfc
	s_sub_i32 s6, s3, s6
	s_lshl_b32 s5, s5, 2
	s_sext_i32_i16 s7, s7
	s_sext_i32_i8 s6, s6
	s_add_i32 s76, s5, s6
	s_ashr_i32 s5, s7, 2
	s_add_i32 s6, s5, 8
	s_cmp_lt_i32 s3, 32
	s_cselect_b32 s82, s5, s6

.LBB0_500:
	s_or_b64 exec, exec, s[8:9]
	s_waitcnt vmcnt(0)
	buffer_inv sc1
	s_waitcnt vmcnt(0)
.LBB0_501:
	s_or_b64 exec, exec, s[0:1]
	v_mov_b32_e32 v79, v184
	s_waitcnt lgkmcnt(0)
	s_barrier
	s_movk_i32 s0, 0x2000
	v_add_u32_e32 v0, s35, v79
	v_ashrrev_i32_e32 v80, 8, v0
	v_cmp_gt_i32_e32 vcc, s0, v80
	s_and_saveexec_b64 s[14:15], vcc
	s_cbranch_execz .LBB0_508

.LBB0_570:
	s_or_b64 exec, exec, s[8:9]
	s_waitcnt vmcnt(0)
	buffer_inv sc1
	s_waitcnt vmcnt(0)
.LBB0_571:
	s_or_b64 exec, exec, s[0:1]
	s_waitcnt vmcnt(4)
	v_mov_b32_e32 v108, v184
	s_waitcnt lgkmcnt(0)
	s_barrier
	v_writelane_b32 v254, s56, 48
	v_readfirstlane_b32 s0, v108
	s_ashr_i32 s20, s0, 6
	s_cmpk_lt_i32 s2, 0xd0
	s_cselect_b64 s[4:5], -1, 0
	s_xor_b64 s[6:7], s[38:39], -1
	s_or_b64 s[4:5], s[4:5], s[6:7]
	v_and_b32_e32 v146, 63, v108
	s_mov_b64 s[0:1], -1
	s_and_b64 vcc, exec, s[4:5]
	v_writelane_b32 v254, s57, 49
	s_cbranch_vccz .LBB0_640

.LBB0_801:
	s_or_b64 exec, exec, s[8:9]
	s_waitcnt vmcnt(0)
	buffer_inv sc1
	s_waitcnt vmcnt(0)
.LBB0_802:
	s_or_b64 exec, exec, s[0:1]
	s_waitcnt vmcnt(9)
	v_mov_b32_e32 v24, v184
	s_waitcnt lgkmcnt(0)
	s_barrier
	s_nop 0
	v_readfirstlane_b32 s0, v24
	s_ashr_i32 s0, s0, 6
	s_add_i32 s14, s0, s76
	s_cmpk_gt_i32 s14, 0x1fff
	s_cbranch_scc1 .LBB0_809
	v_readlane_b32 s80, v254, 26
	s_waitcnt vmcnt(7)
	v_and_b32_e32 v34, 63, v24
	v_readlane_b32 s88, v254, 34
	v_readlane_b32 s89, v254, 35
	v_lshlrev_b32_e32 v32, 6, v34
	v_readlane_b32 s90, v254, 36
	v_readlane_b32 s91, v254, 37
	s_mov_b64 s[8:9], s[88:89]
	s_mov_b64 s[10:11], s[90:91]
	global_load_dwordx4 v[0:3], v32, s[8:9]
	global_load_dwordx4 v[4:7], v32, s[10:11]
	global_load_dwordx4 v[8:11], v32, s[8:9] offset:16
	global_load_dwordx4 v[12:15], v32, s[10:11] offset:16
	global_load_dwordx4 v[16:19], v32, s[8:9] offset:32
	global_load_dwordx4 v[20:23], v32, s[10:11] offset:32
	v_readlane_b32 s86, v254, 32
	v_readlane_b32 s87, v254, 33
	v_and_b32_e32 v33, 60, v24
	s_nop 3
	global_load_dword v144, v33, s[86:87]
	global_load_dwordx4 v[24:27], v32, s[8:9] offset:48
	global_load_dwordx4 v[28:31], v32, s[10:11] offset:48
	v_mov_b32_e32 v33, 0
	s_waitcnt vmcnt(12)
	v_mbcnt_hi_u32_b32 v38, -1, v185
	v_lshlrev_b32_e32 v32, 4, v34
	v_lshlrev_b32_e32 v34, 5, v34
	v_mov_b32_e32 v35, v33
	s_waitcnt vmcnt(11)
	v_and_b32_e32 v40, 64, v38
	v_xor_b32_e32 v39, 1, v38
	v_lshl_add_u64 v[36:37], s[28:29], 0, v[34:35]
	v_lshl_add_u64 v[146:147], s[50:51], 0, v[34:35]
	v_add_u32_e32 v34, 64, v40
	v_xor_b32_e32 v41, 2, v38
	v_cmp_lt_i32_e32 vcc, v39, v34
	v_xor_b32_e32 v42, 4, v38
	v_lshl_add_u64 v[148:149], s[62:63], 0, v[32:33]
	v_cndmask_b32_e32 v32, v38, v39, vcc
	v_cmp_lt_i32_e32 vcc, v41, v34
	v_xor_b32_e32 v43, 8, v38
	s_mov_b64 s[20:21], 0x10500000
	v_cndmask_b32_e32 v33, v38, v41, vcc
	v_cmp_lt_i32_e32 vcc, v42, v34
	s_mov_b64 s[22:23], 0xe500000
	s_waitcnt vmcnt(10)
	v_xor_b32_e32 v44, 16, v38
	v_cndmask_b32_e32 v35, v38, v42, vcc
	v_cmp_lt_i32_e32 vcc, v43, v34
	v_xor_b32_e32 v45, 32, v38
	v_lshl_add_u64 v[150:151], v[36:37], 0, s[20:21]
	v_lshl_add_u64 v[152:153], v[36:37], 0, s[22:23]
	v_cndmask_b32_e32 v36, v38, v43, vcc
	v_cmp_lt_i32_e32 vcc, v44, v34
	s_mov_b64 s[6:7], s[86:87]
	s_mov_b32 s12, 0x3a800000
	v_cndmask_b32_e32 v37, v38, v44, vcc
	v_cmp_lt_i32_e32 vcc, v45, v34
	s_mov_b64 s[0:1], 0x1000000
	s_mov_b32 s3, 0x1000000
	v_cndmask_b32_e32 v34, v38, v45, vcc
	s_mov_b64 s[4:5], 0x2000000
	s_brev_b32 s16, 64
	s_mov_b64 s[6:7], 0x3000000
	s_mov_b32 s17, 0x3000000
	s_mov_b64 s[8:9], 0x1000
	s_movk_i32 s18, 0x1000
	s_mov_b64 s[10:11], 0x1800
	s_mov_b32 s13, 0x3b800000
	s_mov_b32 s19, 0x800000
	v_mov_b32_e32 v155, 0x3000
	v_lshlrev_b32_e32 v170, 2, v32
	v_lshlrev_b32_e32 v171, 2, v33
	v_lshlrev_b32_e32 v172, 2, v35
	v_lshlrev_b32_e32 v173, 2, v36
	v_lshlrev_b32_e32 v174, 2, v37
	v_lshlrev_b32_e32 v175, 2, v34
	v_mov_b32_e32 v154, 0x358637bd
	v_readlane_b32 s81, v254, 27
	v_readlane_b32 s82, v254, 28
	v_readlane_b32 s83, v254, 29
	v_readlane_b32 s84, v254, 30
	v_readlane_b32 s85, v254, 31
	v_readlane_b32 s92, v254, 38
	v_readlane_b32 s93, v254, 39
	v_readlane_b32 s94, v254, 40
	v_readlane_b32 s95, v254, 41
	s_waitcnt vmcnt(2)
	v_mov_b32_e32 v145, v144
	s_branch .LBB0_805

.LBB0_860:
	s_or_b64 exec, exec, s[8:9]
	s_waitcnt vmcnt(0)
	buffer_inv sc1
	s_waitcnt vmcnt(0)
.LBB0_861:
	s_or_b64 exec, exec, s[0:1]
	v_mov_b32_e32 v8, v184
	s_waitcnt lgkmcnt(0)
	s_barrier
	s_and_b64 vcc, exec, s[96:97]
	v_readfirstlane_b32 s4, v8
	s_cbranch_vccnz .LBB0_863
	s_ashr_i32 s0, s2, 31
	s_lshr_b32 s0, s0, 27
	s_add_i32 s0, s2, s0
	s_ashr_i32 s1, s0, 5
	s_and_b32 s0, s0, 0xffe0
	s_sub_i32 s0, s2, s0
	s_bfe_i32 s3, s0, 0x80000
	s_bfe_u32 s3, s3, 0x2000d
	s_add_i32 s3, s0, s3
	s_bfe_i32 s5, s3, 0x80000
	s_and_b32 s3, s3, 0xfc
	s_sub_i32 s0, s0, s3
	s_lshl_b32 s1, s1, 2
	s_sext_i32_i16 s5, s5
	s_sext_i32_i8 s0, s0
	s_add_i32 s54, s1, s0
	s_ashr_i32 s52, s5, 2

.LBB0_992:
	s_or_b64 exec, exec, s[6:7]
	s_mov_b64 s[6:7], exec
	v_mbcnt_lo_u32_b32 v0, s6, 0
	v_mbcnt_hi_u32_b32 v0, s7, v0
	v_cmp_eq_u32_e32 vcc, 0, v0
	s_and_saveexec_b64 s[10:11], vcc
	s_cbranch_execz .LBB0_994
	s_bcnt1_i32_b64 s3, s[6:7]
	v_mov_b32_e32 v0, 0x2000
	v_mov_b32_e32 v1, s3
	global_atomic_add v0, v1, s[4:5] offset:1024
.LBB0_994:
	s_or_b64 exec, exec, s[10:11]
	s_waitcnt vmcnt(0)
	buffer_inv sc1
	s_waitcnt vmcnt(0)
.LBB0_995:
	s_or_b64 exec, exec, s[0:1]
	s_waitcnt lgkmcnt(0)
	v_mov_b32_e32 v0, v184
	s_barrier
	s_nop 0
	v_readfirstlane_b32 s0, v0
	s_ashr_i32 s0, s0, 6
	s_add_i32 s1, s0, s76
	s_cmpk_gt_i32 s1, 0x1fff
	s_cbranch_scc1 .LBB0_998
	v_mbcnt_hi_u32_b32 v1, -1, v185
	v_and_b32_e32 v3, 64, v1
	v_add_u32_e32 v3, 64, v3
	v_xor_b32_e32 v4, 1, v1
	v_cmp_lt_i32_e32 vcc, v4, v3
	s_add_u32 s3, s28, 0x180000
	s_addc_u32 s12, s29, 0
	v_cndmask_b32_e32 v4, v1, v4, vcc
	v_lshlrev_b32_e32 v174, 2, v4
	v_xor_b32_e32 v4, 2, v1
	v_cmp_lt_i32_e32 vcc, v4, v3
	s_ashr_i32 s5, s0, 31
	s_ashr_i32 s6, s76, 31
	v_cndmask_b32_e32 v4, v1, v4, vcc
	v_lshlrev_b32_e32 v175, 2, v4
	v_xor_b32_e32 v4, 4, v1
	v_cmp_lt_i32_e32 vcc, v4, v3
	s_add_u32 s4, s0, s76
	v_and_b32_e32 v0, 63, v0
	v_cndmask_b32_e32 v4, v1, v4, vcc
	v_lshlrev_b32_e32 v176, 2, v4
	v_xor_b32_e32 v4, 8, v1
	v_cmp_lt_i32_e32 vcc, v4, v3
	s_addc_u32 s5, s5, s6
	v_readlane_b32 s80, v254, 10
	v_cndmask_b32_e32 v4, v1, v4, vcc
	v_lshlrev_b32_e32 v177, 2, v4
	v_xor_b32_e32 v4, 16, v1
	v_cmp_lt_i32_e32 vcc, v4, v3
	v_lshlrev_b32_e32 v2, 2, v0
	s_lshl_b64 s[10:11], s[4:5], 11
	v_cndmask_b32_e32 v4, v1, v4, vcc
	v_lshlrev_b32_e32 v178, 2, v4
	v_xor_b32_e32 v4, 32, v1
	v_cmp_lt_i32_e32 vcc, v4, v3
	v_readlane_b32 s81, v254, 11
	v_or_b32_e32 v6, 0x200, v2
	v_cndmask_b32_e32 v1, v1, v4, vcc
	v_or_b32_e32 v4, 0x100, v2
	v_or_b32_e32 v8, 0x300, v2
	v_or_b32_e32 v10, 0x400, v2
	v_or_b32_e32 v12, 0x500, v2
	v_or_b32_e32 v14, 0x600, v2
	v_or_b32_e32 v16, 0x700, v2
	s_ashr_i32 s35, s34, 31
	s_lshl_b64 s[6:7], s[4:5], 12
	v_or_b32_e32 v18, s10, v2
	v_mov_b32_e32 v19, s11
	s_mov_b64 s[10:11], 0x6500400
	v_readlane_b32 s82, v254, 12
	v_readlane_b32 s83, v254, 13
	s_mov_b64 s[36:37], s[80:81]
	v_mov_b32_e32 v129, 0
	s_mov_b32 s1, 0
	v_lshlrev_b32_e32 v179, 2, v1
	v_lshl_or_b32 v130, v0, 3, s6
	v_mov_b32_e32 v131, s7
	s_lshl_b64 s[6:7], s[34:35], 12
	v_lshl_add_u64 v[132:133], v[18:19], 0, s[10:11]
	s_lshl_b64 s[10:11], s[34:35], 11
	s_movk_i32 s13, 0x1000
	v_lshlrev_b32_e32 v128, 4, v0
	s_mov_b32 s14, 0x10500000
	v_lshlrev_b32_e32 v180, 2, v2
	v_lshlrev_b32_e32 v181, 2, v4
	v_lshlrev_b32_e32 v182, 2, v6
	v_lshlrev_b32_e32 v183, 2, v8
	v_lshlrev_b32_e32 v186, 2, v10
	v_lshlrev_b32_e32 v187, 2, v12
	v_lshlrev_b32_e32 v188, 2, v14
	v_lshlrev_b32_e32 v189, 2, v16
	v_mov_b32_e32 v190, 0x358637bd
	s_mov_b32 s15, 0x800000
	s_mov_b32 s16, 0x14900000
	s_mov_b64 s[38:39], s[82:83]
	v_readlane_b32 s84, v254, 14
	v_readlane_b32 s85, v254, 15
	v_readlane_b32 s86, v254, 16
	v_readlane_b32 s87, v254, 17
	v_readlane_b32 s88, v254, 18
	v_readlane_b32 s89, v254, 19
	v_readlane_b32 s90, v254, 20
	v_readlane_b32 s91, v254, 21
	v_readlane_b32 s92, v254, 22
	v_readlane_b32 s93, v254, 23
	v_readlane_b32 s94, v254, 24
	v_readlane_b32 s95, v254, 25

.LBB0_1049:
	s_or_b64 exec, exec, s[10:11]
	s_waitcnt vmcnt(0)
	buffer_inv sc1
	s_waitcnt vmcnt(0)
.LBB0_1050:
	s_or_b64 exec, exec, s[0:1]
	v_mov_b32_e32 v8, v184
	s_cmpk_lt_i32 s2, 0x400
	s_waitcnt lgkmcnt(0)
	s_barrier
	s_cselect_b64 s[0:1], -1, 0
	s_cmpk_gt_i32 s2, 0x3ff
	v_readfirstlane_b32 s4, v8
	s_cbranch_scc1 .LBB0_1052
	s_ashr_i32 s3, s2, 31
	s_lshr_b32 s3, s3, 25
	s_add_i32 s3, s2, s3
	s_ashr_i32 s5, s3, 7
	s_and_b32 s3, s3, 0xff80
	s_sub_i32 s3, s2, s3
	s_bfe_i32 s6, s3, 0x80000
	s_bfe_u32 s6, s6, 0x2000d
	s_add_i32 s6, s3, s6
	s_bfe_i32 s7, s6, 0x80000
	s_and_b32 s6, s6, 0xfc
	s_sub_i32 s3, s3, s6
	s_lshl_b32 s5, s5, 2
	s_sext_i32_i16 s7, s7
	s_sext_i32_i8 s3, s3
	s_add_i32 s46, s5, s3
	s_ashr_i32 s44, s7, 2

.LBB0_1183:
	s_or_b64 exec, exec, s[10:11]
	s_waitcnt vmcnt(0)
	buffer_inv sc1
	s_waitcnt vmcnt(0)
.LBB0_1184:
	s_or_b64 exec, exec, s[0:1]
	v_mov_b32_e32 v8, v184
	s_waitcnt lgkmcnt(0)
	s_barrier
	s_and_b64 vcc, exec, s[96:97]
	v_readfirstlane_b32 s0, v8
	s_cbranch_vccnz .LBB0_1186
	s_ashr_i32 s1, s2, 31
	s_lshr_b32 s1, s1, 27
	s_add_i32 s1, s2, s1
	s_ashr_i32 s3, s1, 5
	s_and_b32 s1, s1, 0xffe0
	s_sub_i32 s1, s2, s1
	s_bfe_i32 s4, s1, 0x80000
	s_bfe_u32 s4, s4, 0x2000d
	s_add_i32 s4, s1, s4
	s_bfe_i32 s5, s4, 0x80000
	s_and_b32 s4, s4, 0xfc
	s_sub_i32 s1, s1, s4
	s_lshl_b32 s3, s3, 2
	s_sext_i32_i16 s5, s5
	s_sext_i32_i8 s1, s1
	s_add_i32 s46, s3, s1
	s_ashr_i32 s44, s5, 2

.LBB0_1315:
	s_or_b64 exec, exec, s[4:5]
	s_mov_b64 s[4:5], exec
	v_mbcnt_lo_u32_b32 v0, s4, 0
	v_mbcnt_hi_u32_b32 v0, s5, v0
	v_cmp_eq_u32_e32 vcc, 0, v0
	s_and_saveexec_b64 s[6:7], vcc
	s_cbranch_execz .LBB0_1317
	s_bcnt1_i32_b64 s4, s[4:5]
	v_mov_b32_e32 v0, 0x2000
	v_mov_b32_e32 v1, s4
	global_atomic_add v0, v1, s[2:3] offset:1024
.LBB0_1317:
	s_or_b64 exec, exec, s[6:7]
	s_waitcnt vmcnt(0)
	buffer_inv sc1
	s_waitcnt vmcnt(0)
.LBB0_1318:
	s_or_b64 exec, exec, s[0:1]
	s_waitcnt lgkmcnt(0)
	s_barrier
	s_nop 0
	v_readfirstlane_b32 s0, v184
	s_ashr_i32 s1, s0, 6
	s_add_i32 s14, s1, s76
	s_cmpk_gt_i32 s14, 0x1fff
	s_cbranch_scc1 .LBB0_1325
	v_and_b32_e32 v2, 63, v184
	v_lshlrev_b32_e32 v64, 3, v2
	v_mov_b32_e32 v65, 0
	v_lshl_add_u64 v[0:1], s[28:29], 0, v[64:65]
	s_mov_b64 s[2:3], 0x14900000
	v_lshl_add_u64 v[68:69], v[0:1], 0, s[2:3]
	v_mbcnt_hi_u32_b32 v1, -1, v185
	v_and_b32_e32 v4, 64, v1
	v_add_u32_e32 v4, 64, v4
	v_xor_b32_e32 v5, 1, v1
	v_cmp_lt_i32_e32 vcc, v5, v4
	v_lshl_add_u64 v[66:67], s[8:9], 0, v[64:65]
	v_readlane_b32 s4, v254, 0
	v_cndmask_b32_e32 v5, v1, v5, vcc
	v_lshlrev_b32_e32 v140, 2, v5
	v_xor_b32_e32 v5, 2, v1
	v_cmp_lt_i32_e32 vcc, v5, v4
	v_readlane_b32 s6, v254, 2
	s_lshl_b32 s0, s30, 4
	v_cndmask_b32_e32 v5, v1, v5, vcc
	v_lshlrev_b32_e32 v141, 2, v5
	v_xor_b32_e32 v5, 4, v1
	v_cmp_lt_i32_e32 vcc, v5, v4
	s_ashr_i32 s2, s1, 31
	s_ashr_i32 s4, s76, 31
	v_readlane_b32 s7, v254, 3
	v_cndmask_b32_e32 v5, v1, v5, vcc
	s_add_u32 s6, s1, s76
	v_readlane_b32 s5, v254, 1
	v_lshlrev_b32_e32 v142, 2, v5
	v_xor_b32_e32 v5, 8, v1
	s_addc_u32 s7, s2, s4
	v_readlane_b32 s10, v254, 6
	v_cmp_lt_i32_e32 vcc, v5, v4
	s_lshl_b64 s[4:5], s[6:7], 13
	v_readlane_b32 s11, v254, 7
	v_cndmask_b32_e32 v5, v1, v5, vcc
	s_add_u32 s4, s10, s4
	v_lshlrev_b32_e32 v0, 2, v2
	v_lshlrev_b32_e32 v2, 4, v2
	v_mov_b32_e32 v3, v65
	v_lshlrev_b32_e32 v143, 2, v5
	v_xor_b32_e32 v5, 16, v1
	s_addc_u32 s5, s11, s5
	v_lshl_add_u64 v[70:71], s[10:11], 0, v[2:3]
	v_cmp_lt_i32_e32 vcc, v5, v4
	v_lshl_add_u64 v[2:3], s[4:5], 0, v[2:3]
	s_mov_b64 s[4:5], 0x1000
	s_ashr_i32 s1, s0, 31
	v_cndmask_b32_e32 v5, v1, v5, vcc
	v_lshl_add_u64 v[72:73], v[2:3], 0, s[4:5]
	s_lshl_b64 s[4:5], s[0:1], 13
	s_lshl_b64 s[6:7], s[6:7], 12
	v_lshlrev_b32_e32 v144, 2, v5
	v_xor_b32_e32 v5, 32, v1
	s_add_u32 s6, s28, s6
	v_cmp_lt_i32_e32 vcc, v5, v4
	s_addc_u32 s7, s29, s7
	v_readlane_b32 s8, v254, 4
	v_readlane_b32 s9, v254, 5
	v_cndmask_b32_e32 v1, v1, v5, vcc
	v_lshl_add_u64 v[2:3], s[6:7], 0, v[64:65]
	s_mov_b64 s[6:7], 0x10500000
	s_mov_b32 s3, 0
	v_lshlrev_b32_e32 v145, 2, v1
	v_lshl_add_u64 v[74:75], v[2:3], 0, s[6:7]
	s_lshl_b64 s[6:7], s[0:1], 12
	v_lshlrev_b32_e32 v64, 2, v0
	s_mov_b64 s[8:9], 0x184000
	s_mov_b32 s1, 0x4400000
	s_mov_b32 s15, 0x184000
	s_mov_b32 s16, 0x185000
	v_mov_b32_e32 v146, 0x358637bd
	s_mov_b32 s17, 0x800000
	s_movk_i32 s18, 0x1000
	s_branch .LBB0_1321
